# grid barrier: members poll the top-level generation directly, per-XCD generation hop and its atomic removed (9 in-loop barrier copies); on top of v50
# speedup vs baseline: 1.0070x; 1.0070x over previous
; __device__ __forceinline__ unsigned xb_ld(unsigned* p)              { return __hip_atomic_load(p, __ATOMIC_RELAXED, __HIP_MEMORY_SCOPE_AGENT); }
; __device__ __forceinline__ unsigned xb_add(unsigned* p, unsigned v) { return __hip_atomic_fetch_add(p, v, __ATOMIC_RELAXED, __HIP_MEMORY_SCOPE_AGENT); }
; #define XB_SPIN(cond, bar) do { unsigned _sp = 0; while (cond) { __builtin_amdgcn_s_sleep(1); \
;     if ((++_sp & 255u) == 0u) { if (xb_ld(&(bar)[XB_TMO])) break; if (_sp > XB_SPIN_CAP) { atomicAdd(&(bar)[XB_TMO], 1u); break; } } } } while (0)
; __device__ __forceinline__ void xcd_barrier_complete(unsigned* bar, unsigned x, unsigned& nloc, unsigned& nx) {
;     const unsigned G = gridDim.x * gridDim.y * gridDim.z;
;     unsigned sum, cnt, mine, sp = 0u;
;     for (;;) {
;         sum = 0u; cnt = 0u; mine = 0u;
; #pragma unroll
;         for (unsigned j = 0; j < 16; ++j) { const unsigned c = xb_ld(&bar[XB_XCNT(j)]); sum += c; cnt += (c > 0u) ? 1u : 0u; mine = (j == x) ? c : mine; }
;         if (sum == G) break;
;         __builtin_amdgcn_s_sleep(1);
;         if ((++sp & 255u) == 0u) { if (xb_ld(&bar[XB_TMO])) break; if (sp > XB_SPIN_CAP) { atomicAdd(&bar[XB_TMO], 1u); break; } }
;     }
;     nloc = mine > 0u ? mine : 1u; nx = cnt > 0u ? cnt : 1u;
; }
; __device__ __forceinline__ void xcd_barrier(const XcdBarrier& b) {
;     asm volatile("s_waitcnt vmcnt(0)" ::: "memory");
;     __syncthreads();
;     if (threadIdx.x == 0) {
;         unsigned* bar = b.bar;
;         __builtin_amdgcn_s_waitcnt(0);
;         unsigned nloc = b.st[0], nx = b.st[1];
;         if (nloc == 0u) { xcd_barrier_complete(bar, b.x, nloc, nx); b.st[0] = nloc; b.st[1] = nx; }
;         const unsigned old = xb_add(&bar[XB_XSUB(b.x)], 1u);
;         const unsigned gen = old / nloc;
;         if (old + 1u == (gen + 1u) * nloc) {
;             __builtin_amdgcn_fence(__ATOMIC_RELEASE, "agent");
;             asm volatile("s_waitcnt vmcnt(0)" ::: "memory");
;             const unsigned og = xb_add(&bar[XB_TOP], 1u);
;             const unsigned tg = og / nx;
;             if (og + 1u == (tg + 1u) * nx) xb_add(&bar[XB_TOPGEN], 1u);
;             else XB_SPIN(xb_ld(&bar[XB_TOPGEN]) == tg, bar);
;             __builtin_amdgcn_fence(__ATOMIC_ACQUIRE, "agent");
;             xb_add(&bar[XB_XGEN(b.x)], 1u);
;             asm volatile("s_waitcnt vmcnt(0)" ::: "memory");
.LBB0_570:
	s_or_b64 exec, exec, s[2:3]
	s_barrier
	s_load_dwordx2 s[10:11], s[0:1], 0x110
	v_lshl_add_u64 v[0:1], v[0:1], 2, s[38:39]
	s_mov_b32 s93, 0
	s_mov_b32 s94, s93
	s_mov_b32 s95, s93
	s_waitcnt lgkmcnt(0)
	s_lshr_b32 s75, s10, 3
	s_add_u32 s80, s68, 0xf800200
	s_addc_u32 s81, s69, 0
	s_add_u32 s6, s68, 0xf800400
	s_mul_i32 s2, s11, s10
	s_addc_u32 s7, s69, 0
	s_mul_i32 s76, s2, s33
	s_add_u32 s2, s68, 0xf800500
	s_addc_u32 s3, s69, 0
	v_writelane_b32 v241, s2, 4
	s_mov_b32 s92, s93
	v_mov_b64_e32 v[238:239], s[94:95]
	v_writelane_b32 v241, s3, 5
	s_add_u32 s2, s68, 0xf800600
	s_addc_u32 s3, s69, 0
	v_writelane_b32 v241, s2, 6
	v_mov_b64_e32 v[236:237], s[92:93]
	s_mov_b64 s[94:95], s[6:7]
	v_writelane_b32 v241, s3, 7
	s_add_u32 s2, s68, 0xf800700
	s_addc_u32 s3, s69, 0
	v_writelane_b32 v241, s2, 8
	s_mov_b32 s88, 0.5
	s_movk_i32 s86, 0xff80
	v_writelane_b32 v241, s3, 9
	s_add_u32 s2, s68, 0xf800800
	s_addc_u32 s3, s69, 0
	v_writelane_b32 v241, s2, 10
	v_and_b32_e32 v186, 0xff, v175
	v_mov_b32_e32 v12, 0
	v_writelane_b32 v241, s3, 11
	s_add_u32 s2, s68, 0xf800900
	s_addc_u32 s3, s69, 0
	v_writelane_b32 v241, s2, 12
	v_mov_b32_e32 v187, 0x358637bd
	v_mov_b32_e32 v188, 0x25000
	v_writelane_b32 v241, s3, 13
	s_add_u32 s2, s68, 0xf800a00
	s_addc_u32 s3, s69, 0
	v_writelane_b32 v241, s2, 14
	v_mov_b32_e32 v189, 0x25004
	v_mov_b32_e32 v190, 1
	v_writelane_b32 v241, s3, 15
	s_add_u32 s2, s68, 0xf800b00
	s_addc_u32 s3, s69, 0
	v_writelane_b32 v241, s2, 16
	v_mov_b32_e32 v192, 0x3ecc95a3
	s_mov_b32 s89, 0x3eaaaaab
	v_writelane_b32 v241, s3, 17
	s_add_u32 s2, s68, 0xf800c00
	s_addc_u32 s3, s69, 0
	v_writelane_b32 v241, s2, 18
	v_not_b32_e32 v193, 63
	v_mov_b32_e32 v194, 0xff800000
	v_writelane_b32 v241, s3, 19
	s_add_u32 s2, s68, 0xf800d00
	s_addc_u32 s3, s69, 0
	v_writelane_b32 v241, s2, 20
	v_mov_b32_e32 v195, 0x1680000
	v_mov_b32_e32 v196, 0x12800
	v_writelane_b32 v241, s3, 21
	s_add_u32 s2, s68, 0xf800e00
	s_addc_u32 s3, s69, 0
	v_writelane_b32 v241, s2, 22
	v_mov_b32_e32 v197, 0x41b17218
	v_mov_b32_e32 v198, 0x48
	v_writelane_b32 v241, s3, 23
	s_add_u32 s2, s68, 0xf800f00
	s_addc_u32 s3, s69, 0
	v_writelane_b32 v241, s2, 24
	v_mov_b32_e32 v199, 0x7f800000
	v_mov_b32_e32 v200, 0x7fc00000
	v_writelane_b32 v241, s3, 25
	s_add_u32 s2, s68, 0xf801000
	s_addc_u32 s3, s69, 0
	v_writelane_b32 v241, s2, 26
	s_mov_b32 s82, 0x10000
	s_mov_b32 s33, 0x800000
	v_writelane_b32 v241, s3, 27
	s_add_u32 s2, s68, 0xf801100
	s_addc_u32 s3, s69, 0
	v_writelane_b32 v241, s2, 28
	s_movk_i32 s83, 0xc00
	s_movk_i32 s14, 0x1000
	v_writelane_b32 v241, s3, 29
	s_add_u32 s2, s68, 0xf801200
	s_addc_u32 s3, s69, 0
	s_add_u32 s78, s68, 0xf801300
	s_addc_u32 s79, s69, 0
	v_writelane_b32 v241, s2, 30
	s_cmp_eq_u32 s64, 15
	s_cselect_b64 s[4:5], -1, 0
	v_writelane_b32 v241, s3, 31
	v_writelane_b32 v241, s4, 32
	s_cmp_eq_u32 s64, 14
	s_mov_b32 s2, 0x20000
	v_writelane_b32 v241, s5, 33
	s_cselect_b64 s[4:5], -1, 0
	v_writelane_b32 v241, s4, 34
	s_cmp_eq_u32 s64, 13
	s_movk_i32 s15, 0x810
	v_writelane_b32 v241, s5, 35
	s_cselect_b64 s[4:5], -1, 0
	v_writelane_b32 v241, s4, 36
	s_cmp_eq_u32 s64, 12
	s_movk_i32 s16, 0x80f
	v_writelane_b32 v241, s5, 37
	s_cselect_b64 s[4:5], -1, 0
	v_writelane_b32 v241, s4, 38
	s_cmp_eq_u32 s64, 11
	s_mov_b32 s17, 0xff800000
	v_writelane_b32 v241, s5, 39
	s_cselect_b64 s[4:5], -1, 0
	v_writelane_b32 v241, s4, 40
	s_cmp_eq_u32 s64, 10
	s_mov_b32 s18, 0xbfb8aa3b
	v_writelane_b32 v241, s5, 41
	s_cselect_b64 s[4:5], -1, 0
	v_writelane_b32 v241, s4, 42
	s_cmp_eq_u32 s64, 9
	s_movk_i32 s19, 0x110
	v_writelane_b32 v241, s5, 43
	s_cselect_b64 s[4:5], -1, 0
	v_writelane_b32 v241, s4, 44
	s_cmp_eq_u32 s64, 8
	s_mov_b32 s20, 0x3f317217
	v_writelane_b32 v241, s5, 45
	s_cselect_b64 s[4:5], -1, 0
	v_writelane_b32 v241, s4, 46
	s_cmp_eq_u32 s64, 7
	s_mov_b32 s21, 0x7f800000
	v_writelane_b32 v241, s5, 47
	s_cselect_b64 s[4:5], -1, 0
	v_writelane_b32 v241, s4, 48
	s_cmp_eq_u32 s64, 6
	s_mov_b32 s22, 0xfffffe0
	v_writelane_b32 v241, s5, 49
	s_cselect_b64 s[4:5], -1, 0
	v_writelane_b32 v241, s4, 50
	s_cmp_eq_u32 s64, 5
	s_movk_i32 s23, 0x80e
	v_writelane_b32 v241, s5, 51
	s_cselect_b64 s[4:5], -1, 0
	v_writelane_b32 v241, s4, 52
	s_cmp_eq_u32 s64, 4
	s_movk_i32 s24, 0x80d
	v_writelane_b32 v241, s5, 53
	s_cselect_b64 s[4:5], -1, 0
	v_writelane_b32 v241, s4, 54
	s_cmp_eq_u32 s64, 3
	s_movk_i32 s25, 0x80c
	v_writelane_b32 v241, s5, 55
	s_cselect_b64 s[4:5], -1, 0
	v_writelane_b32 v241, s4, 56
	s_cmp_eq_u32 s64, 2
	s_movk_i32 s26, 0x80b
	v_writelane_b32 v241, s5, 57
	s_cselect_b64 s[4:5], -1, 0
	v_writelane_b32 v241, s4, 58
	s_cmp_eq_u32 s64, 1
	s_movk_i32 s27, 0x80a
	v_writelane_b32 v241, s5, 59
	s_cselect_b64 s[4:5], -1, 0
	v_writelane_b32 v241, s4, 60
	s_cmp_eq_u32 s64, 0
	s_movk_i32 s28, 0x809
	v_writelane_b32 v241, s5, 61
	s_cselect_b64 s[4:5], -1, 0
	s_add_u32 s8, s68, 0xf803400
	s_addc_u32 s9, s69, 0
	v_writelane_b32 v240, s8, 0
	v_writelane_b32 v241, s4, 62
	s_mov_b32 s29, 0xbca3d70a
	v_writelane_b32 v240, s9, 1
	s_add_u32 s8, s68, 0xf803500
	s_addc_u32 s9, s69, 0
	s_abs_i32 s77, s10
	v_cvt_f32_u32_e32 v2, s77
	v_writelane_b32 v241, s5, 63
	s_mov_b64 s[4:5], 0x1400
	v_lshl_add_u64 v[164:165], v[0:1], 0, s[4:5]
	v_rcp_iflag_f32_e32 v2, v2
	s_mov_b64 s[4:5], 0x2400
	v_lshl_add_u64 v[166:167], v[0:1], 0, s[4:5]
	v_writelane_b32 v240, s8, 2
	v_mul_f32_e32 v0, 0x4f7ffffe, v2
	v_cvt_u32_f32_e32 v0, v0
	v_writelane_b32 v240, s9, 3
	s_lshr_b32 s4, s10, 1
	v_writelane_b32 v240, s4, 4
	s_sub_i32 s4, 0, s77
	v_readfirstlane_b32 s5, v0
	s_mul_i32 s4, s4, s5
	s_mul_hi_u32 s4, s5, s4
	s_add_i32 s4, s5, s4
	s_lshl_b32 s84, s10, 1
	v_writelane_b32 v240, s4, 5
	s_lshl_b32 s4, s10, 8
	v_writelane_b32 v240, s4, 6
	s_mul_i32 s4, s10, 0x600
	s_mul_hi_i32 s5, s84, 0x300
	s_ashr_i32 s85, s84, 31
	v_writelane_b32 v240, s4, 7
	s_ashr_i32 s8, s10, 31
	v_mbcnt_lo_u32_b32 v0, -1, 0
	v_writelane_b32 v240, s5, 8
	s_lshl_b64 s[4:5], s[84:85], 8
	v_writelane_b32 v240, s4, 9
	v_readlane_b32 s70, v241, 1
	v_mbcnt_hi_u32_b32 v191, -1, v0
	v_writelane_b32 v240, s5, 10
	s_lshl_b64 s[4:5], s[84:85], 11
	v_writelane_b32 v240, s4, 11
	s_mov_b32 s87, -1
	s_mov_b64 s[90:91], 0x1800
	v_writelane_b32 v240, s5, 12
	s_lshl_b64 s[4:5], s[84:85], 13
	v_writelane_b32 v240, s4, 13
	v_readlane_b32 s68, v241, 0
	v_readlane_b32 s71, v241, 2
	v_writelane_b32 v240, s5, 14
	s_lshl_b64 s[4:5], s[84:85], 12
	v_writelane_b32 v240, s4, 15
	v_readlane_b32 s69, v241, 3
	s_nop 0
	v_writelane_b32 v240, s5, 16
	s_lshl_b64 s[4:5], s[84:85], 9
	v_writelane_b32 v240, s4, 17
	s_mov_b32 s85, s8
	s_nop 0
	v_writelane_b32 v240, s5, 18
	v_writelane_b32 v240, s75, 19
	v_writelane_b32 v240, s76, 20
	v_writelane_b32 v240, s80, 21
	s_mov_b64 s[4:5], 0
	s_nop 0
	v_writelane_b32 v240, s81, 22
	v_writelane_b32 v240, s94, 23
	s_nop 1
	v_writelane_b32 v240, s95, 24
	v_writelane_b32 v240, s77, 25
	v_writelane_b32 v240, s85, 26
	s_branch .LBB0_575
.LBB0_571:
	s_or_b64 exec, exec, s[12:13]
	s_waitcnt vmcnt(0)
	buffer_inv sc1
	s_waitcnt vmcnt(0)
.LBB0_572:
	s_or_b64 exec, exec, s[6:7]

; __device__ __forceinline__ unsigned xb_ld(unsigned* p)              { return __hip_atomic_load(p, __ATOMIC_RELAXED, __HIP_MEMORY_SCOPE_AGENT); }
; __device__ __forceinline__ unsigned xb_add(unsigned* p, unsigned v) { return __hip_atomic_fetch_add(p, v, __ATOMIC_RELAXED, __HIP_MEMORY_SCOPE_AGENT); }
; #define XB_SPIN(cond, bar) do { unsigned _sp = 0; while (cond) { __builtin_amdgcn_s_sleep(1); \
;     if ((++_sp & 255u) == 0u) { if (xb_ld(&(bar)[XB_TMO])) break; if (_sp > XB_SPIN_CAP) { atomicAdd(&(bar)[XB_TMO], 1u); break; } } } } while (0)
; __device__ __forceinline__ void xcd_barrier(const XcdBarrier& b) {
;     ...
;         const unsigned old = xb_add(&bar[XB_XSUB(b.x)], 1u);
;         const unsigned gen = old / nloc;
;         if (old + 1u == (gen + 1u) * nloc) {
;             __builtin_amdgcn_fence(__ATOMIC_RELEASE, "agent");
;             asm volatile("s_waitcnt vmcnt(0)" ::: "memory");
;             const unsigned og = xb_add(&bar[XB_TOP], 1u);
;             const unsigned tg = og / nx;
;             if (og + 1u == (tg + 1u) * nx) xb_add(&bar[XB_TOPGEN], 1u);
;             else XB_SPIN(xb_ld(&bar[XB_TOPGEN]) == tg, bar);
;             __builtin_amdgcn_fence(__ATOMIC_ACQUIRE, "agent");
;             xb_add(&bar[XB_XGEN(b.x)], 1u);
;             asm volatile("s_waitcnt vmcnt(0)" ::: "memory");
;         } else {
;             XB_SPIN(xb_ld(&bar[XB_XGEN(b.x)]) == gen, bar);
.LBB0_652:
	global_atomic_add v3, v[164:165], v190, off sc0
	v_cvt_f32_u32_e32 v1, v2
	v_sub_u32_e32 v4, 0, v2
	v_rcp_iflag_f32_e32 v1, v1
	s_nop 0
	v_mul_f32_e32 v1, 0x4f7ffffe, v1
	v_cvt_u32_f32_e32 v1, v1
	v_mul_lo_u32 v4, v4, v1
	v_mul_hi_u32 v4, v1, v4
	v_add_u32_e32 v1, v1, v4
	s_waitcnt vmcnt(0)
	v_mul_hi_u32 v1, v3, v1
	v_mul_lo_u32 v4, v1, v2
	v_sub_u32_e32 v4, v3, v4
	v_add_u32_e32 v5, 1, v1
	v_cmp_ge_u32_e32 vcc, v4, v2
	v_add_u32_e32 v3, 1, v3
	s_nop 0
	v_cndmask_b32_e32 v1, v1, v5, vcc
	v_sub_u32_e32 v5, v4, v2
	v_cndmask_b32_e32 v4, v4, v5, vcc
	v_add_u32_e32 v5, 1, v1
	v_cmp_ge_u32_e32 vcc, v4, v2
	s_nop 1
	v_cndmask_b32_e32 v1, v1, v5, vcc
	v_mul_lo_u32 v4, v2, v1
	v_add_u32_e32 v2, v4, v2
	v_cmp_ne_u32_e32 vcc, v3, v2
	s_and_saveexec_b64 s[6:7], vcc
	s_xor_b64 s[6:7], exec, s[6:7]
	s_cbranch_execz .LBB0_666
	s_waitcnt lgkmcnt(0)
	v_readlane_b32 s100, v240, 2
	v_readlane_b32 s101, v240, 3
	s_nop 4
	global_load_dword v0, v12, s[100:101] sc1
	s_waitcnt vmcnt(0)
	v_cmp_eq_u32_e32 vcc, v0, v1
	s_and_saveexec_b64 s[12:13], vcc
	s_cbranch_execz .LBB0_665
	s_mov_b32 s8, 1
	s_mov_b64 s[38:39], 0
	s_branch .LBB0_656

; __device__ __forceinline__ unsigned xb_ld(unsigned* p)              { return __hip_atomic_load(p, __ATOMIC_RELAXED, __HIP_MEMORY_SCOPE_AGENT); }
; #define XB_SPIN(cond, bar) do { unsigned _sp = 0; while (cond) { __builtin_amdgcn_s_sleep(1); \
;     if ((++_sp & 255u) == 0u) { if (xb_ld(&(bar)[XB_TMO])) break; if (_sp > XB_SPIN_CAP) { atomicAdd(&(bar)[XB_TMO], 1u); break; } } } } while (0)
; __device__ __forceinline__ void xcd_barrier(const XcdBarrier& b) {
;     ...
;             XB_SPIN(xb_ld(&bar[XB_XGEN(b.x)]) == gen, bar);
.LBB0_658:
	global_load_dword v0, v12, s[100:101] sc1
	s_add_i32 s8, s8, 1
	s_mov_b64 s[44:45], -1
	s_waitcnt vmcnt(0)
	v_cmp_ne_u32_e32 vcc, v0, v1
	s_orn2_b64 s[42:43], vcc, exec
	s_branch .LBB0_655

; __device__ __forceinline__ unsigned xb_ld(unsigned* p)              { return __hip_atomic_load(p, __ATOMIC_RELAXED, __HIP_MEMORY_SCOPE_AGENT); }
; __device__ __forceinline__ unsigned xb_add(unsigned* p, unsigned v) { return __hip_atomic_fetch_add(p, v, __ATOMIC_RELAXED, __HIP_MEMORY_SCOPE_AGENT); }
; #define XB_SPIN(cond, bar) do { unsigned _sp = 0; while (cond) { __builtin_amdgcn_s_sleep(1); \
;     if ((++_sp & 255u) == 0u) { if (xb_ld(&(bar)[XB_TMO])) break; if (_sp > XB_SPIN_CAP) { atomicAdd(&(bar)[XB_TMO], 1u); break; } } } } while (0)
; __device__ __forceinline__ void xcd_barrier(const XcdBarrier& b) {
;     ...
;             else XB_SPIN(xb_ld(&bar[XB_TOPGEN]) == tg, bar);
;             __builtin_amdgcn_fence(__ATOMIC_ACQUIRE, "agent");
;             xb_add(&bar[XB_XGEN(b.x)], 1u);
;             asm volatile("s_waitcnt vmcnt(0)" ::: "memory");
.LBB0_681:
	s_or_b64 exec, exec, s[12:13]
	s_and_saveexec_b64 s[12:13], s[38:39]
	s_cbranch_execz .LBB0_683
	global_atomic_add v[0:1], v190, off
.LBB0_683:
	s_or_b64 exec, exec, s[12:13]
	s_waitcnt vmcnt(0)
	buffer_inv sc1
	s_waitcnt vmcnt(0)
.LBB0_684:
	s_or_b64 exec, exec, s[6:7]

; __device__ __forceinline__ unsigned xb_ld(unsigned* p)              { return __hip_atomic_load(p, __ATOMIC_RELAXED, __HIP_MEMORY_SCOPE_AGENT); }
; __device__ __forceinline__ unsigned xb_add(unsigned* p, unsigned v) { return __hip_atomic_fetch_add(p, v, __ATOMIC_RELAXED, __HIP_MEMORY_SCOPE_AGENT); }
; #define XB_SPIN(cond, bar) do { unsigned _sp = 0; while (cond) { __builtin_amdgcn_s_sleep(1); \
;     if ((++_sp & 255u) == 0u) { if (xb_ld(&(bar)[XB_TMO])) break; if (_sp > XB_SPIN_CAP) { atomicAdd(&(bar)[XB_TMO], 1u); break; } } } } while (0)
; __device__ __forceinline__ void xcd_barrier(const XcdBarrier& b) {
;     ...
;             else XB_SPIN(xb_ld(&bar[XB_TOPGEN]) == tg, bar);
;             __builtin_amdgcn_fence(__ATOMIC_ACQUIRE, "agent");
;             xb_add(&bar[XB_XGEN(b.x)], 1u);
;             asm volatile("s_waitcnt vmcnt(0)" ::: "memory");
.LBB0_830:
	s_or_b64 exec, exec, s[12:13]
	s_and_saveexec_b64 s[12:13], s[38:39]
	s_cbranch_execz .LBB0_832
	global_atomic_add v[0:1], v190, off
.LBB0_832:
	s_or_b64 exec, exec, s[12:13]
	s_waitcnt vmcnt(0)
	buffer_inv sc1
	s_waitcnt vmcnt(0)
.LBB0_833:
	s_or_b64 exec, exec, s[6:7]

; __device__ __forceinline__ unsigned xb_add(unsigned* p, unsigned v) { return __hip_atomic_fetch_add(p, v, __ATOMIC_RELAXED, __HIP_MEMORY_SCOPE_AGENT); }
; __device__ __forceinline__ void xcd_barrier(const XcdBarrier& b) {
;     ...
;             __builtin_amdgcn_fence(__ATOMIC_ACQUIRE, "agent");
;             xb_add(&bar[XB_XGEN(b.x)], 1u);
;             asm volatile("s_waitcnt vmcnt(0)" ::: "memory");
.LBB0_932:
	s_or_b64 exec, exec, s[6:7]
	s_waitcnt vmcnt(0)
	buffer_inv sc1
	s_waitcnt vmcnt(0)

; __device__ __forceinline__ unsigned xb_ld(unsigned* p)              { return __hip_atomic_load(p, __ATOMIC_RELAXED, __HIP_MEMORY_SCOPE_AGENT); }
; __device__ __forceinline__ unsigned xb_add(unsigned* p, unsigned v) { return __hip_atomic_fetch_add(p, v, __ATOMIC_RELAXED, __HIP_MEMORY_SCOPE_AGENT); }
; #define XB_SPIN(cond, bar) do { unsigned _sp = 0; while (cond) { __builtin_amdgcn_s_sleep(1); \
;     if ((++_sp & 255u) == 0u) { if (xb_ld(&(bar)[XB_TMO])) break; if (_sp > XB_SPIN_CAP) { atomicAdd(&(bar)[XB_TMO], 1u); break; } } } } while (0)
; __device__ __forceinline__ void xcd_barrier(const XcdBarrier& b) {
;     ...
;             else XB_SPIN(xb_ld(&bar[XB_TOPGEN]) == tg, bar);
;             __builtin_amdgcn_fence(__ATOMIC_ACQUIRE, "agent");
;             xb_add(&bar[XB_XGEN(b.x)], 1u);
;             asm volatile("s_waitcnt vmcnt(0)" ::: "memory");
.LBB0_1028:
	s_or_b64 exec, exec, s[12:13]
	s_and_saveexec_b64 s[12:13], s[38:39]
	s_cbranch_execz .LBB0_1030
	global_atomic_add v[0:1], v190, off
.LBB0_1030:
	s_or_b64 exec, exec, s[12:13]
	s_waitcnt vmcnt(0)
	buffer_inv sc1
	s_waitcnt vmcnt(0)
.LBB0_1031:
	s_or_b64 exec, exec, s[6:7]

; __device__ __forceinline__ unsigned xb_ld(unsigned* p)              { return __hip_atomic_load(p, __ATOMIC_RELAXED, __HIP_MEMORY_SCOPE_AGENT); }
; __device__ __forceinline__ unsigned xb_add(unsigned* p, unsigned v) { return __hip_atomic_fetch_add(p, v, __ATOMIC_RELAXED, __HIP_MEMORY_SCOPE_AGENT); }
; #define XB_SPIN(cond, bar) do { unsigned _sp = 0; while (cond) { __builtin_amdgcn_s_sleep(1); \
;     if ((++_sp & 255u) == 0u) { if (xb_ld(&(bar)[XB_TMO])) break; if (_sp > XB_SPIN_CAP) { atomicAdd(&(bar)[XB_TMO], 1u); break; } } } } while (0)
; __device__ __forceinline__ void xcd_barrier(const XcdBarrier& b) {
;     ...
;             else XB_SPIN(xb_ld(&bar[XB_TOPGEN]) == tg, bar);
;             __builtin_amdgcn_fence(__ATOMIC_ACQUIRE, "agent");
;             xb_add(&bar[XB_XGEN(b.x)], 1u);
;             asm volatile("s_waitcnt vmcnt(0)" ::: "memory");
.LBB0_1191:
	s_or_b64 exec, exec, s[12:13]
	s_and_saveexec_b64 s[12:13], s[38:39]
	s_cbranch_execz .LBB0_1193
	global_atomic_add v[0:1], v190, off
.LBB0_1193:
	s_or_b64 exec, exec, s[12:13]
	s_waitcnt vmcnt(0)
	buffer_inv sc1
	s_waitcnt vmcnt(0)
.LBB0_1194:
	s_or_b64 exec, exec, s[6:7]
